# attention: context unit first + XCD-local latent unit order
# baseline (speedup 1.0000x reference)
; #define LAS __attribute__((address_space(3)))
; __device__ __forceinline__ void attn_mfma(LAS unsigned char* lds, int layer, int G, const int wave_s) {
;     ...
;     const bf16_t* Q = (const bf16_t*)(ws + WS_Q); const bf16_t* Kb = (const bf16_t*)(ws + WS_K); const bf16_t* Vb = (const bf16_t*)(ws + WS_V);
;     bf16_t* YM = (bf16_t*)(ws + WS_YM); const float* ZT = (const float*)(ws + WS_SSHY);
;     const float* gat = Pp->in[20] + layer * ATTW; const float* ghy = Pp->in[19] + layer * HY;
;     const int r32 = lane & 31, hi = lane >> 5, h = wave, kv = h >> 2;
;     const float sk = Pp->in[18][layer * NH + h] * LOG2E;
;     const unsigned lbase = (unsigned)(uintptr_t)lds;
;     LAS float* al_l = (LAS float*)(lds + AT_SCR) + wave * 64; LAS float* li_l = al_l + 32;
;     LAS float* xa = (LAS float*)(lds + AT_XA); LAS float* xh = (LAS float*)(lds + AT_XH);
;     const int nunits = layer == DEPTH - 1 ? ML / 32 : MT / 32;
;     for (int unit = blockIdx.x; unit < nunits; unit += G) {
.LBB0_785:
	s_andn2_b64 vcc, exec, s[36:37]
	s_cbranch_vccnz .LBB0_884
	s_cmp_lg_u32 s76, 3
	s_cselect_b64 s[44:45], -1, 0
	s_and_b64 s[0:1], s[44:45], exec
	s_movk_i32 s0, 0x110
	s_cselect_b32 s0, s0, 0x100
	s_cmp_ge_i32 s2, s0
	v_readlane_b32 s17, v253, 2
	s_mov_b64 s[36:37], s[94:95]
	v_mbcnt_lo_u32_b32 v0, -1, 0
	v_mbcnt_hi_u32_b32 v0, -1, v0
	s_cbranch_scc1 .LBB0_826
	s_load_dwordx2 s[40:41], s[36:37], 0xd8
	s_lshl_b32 s10, s76, 3
	s_lshl_b32 s1, s17, 6
	v_and_b32_e32 v184, 31, v0
	s_waitcnt vmcnt(0)
	v_lshlrev_b32_e32 v4, 4, v0
	s_waitcnt lgkmcnt(0)
	s_add_u32 s46, s40, 0xac20000
	s_addc_u32 s47, s41, 0
	s_add_u32 s48, s40, 0xb060000
	s_addc_u32 s49, s41, 0
	s_add_u32 s42, s40, 0xb4a0000
	s_addc_u32 s43, s41, 0
	s_add_i32 s10, s17, s10
	s_ashr_i32 s11, s10, 31
	s_lshl_b64 s[38:39], s[10:11], 2
	s_load_dwordx2 s[10:11], s[36:37], 0x90
	s_load_dwordx4 s[52:55], s[36:37], 0x98
	v_and_b32_e32 v6, 0xc0, v4
	v_lshlrev_b32_e32 v7, 1, v0
	v_and_b32_e32 v7, 32, v7
	s_waitcnt lgkmcnt(0)
	s_add_u32 s10, s10, s38
	s_addc_u32 s11, s11, s39
	global_load_dword v2, v1, s[10:11]
	s_lshl_b32 s10, s17, 8
	s_add_i32 s15, s10, 0
	s_lshl_b32 s26, s76, 10
	s_add_i32 s15, s15, 0x20000
	s_lshl_b64 s[10:11], s[26:27], 2
	s_add_u32 s56, s52, s10
	s_addc_u32 s57, s53, s11
	s_add_u32 s54, s54, s10
	s_addc_u32 s55, s55, s11
	s_lshl_b32 s60, s17, 7
	s_ashr_i32 s61, s60, 31
	s_lshl_b64 s[52:53], s[60:61], 1
	s_add_u32 s10, s40, s52
	s_addc_u32 s11, s41, s53
	s_add_u32 s50, s10, 0x9b20000
	s_addc_u32 s51, s11, 0
	s_lshl_b32 s10, s17, 12
	s_and_b32 s10, s10, 0xffffc000
	s_add_i32 s11, s10, 0
	v_lshl_add_u32 v188, v184, 8, s11
	s_add_i32 s11, 0, 0x8000
	v_add_u32_e32 v6, s11, v6
	v_ashrrev_i32_e32 v185, 5, v0
	v_mov_b32_e32 v163, v1
	s_mulk_i32 s17, 0x2200
	v_lshlrev_b32_e32 v187, 4, v185
	v_cmp_gt_u32_e64 s[36:37], 32, v0
	s_mov_b64 s[28:29], 0xd6a0000
	s_add_i32 s17, s17, 0
	v_ashrrev_i32_e32 v194, 4, v0
	v_lshl_add_u32 v193, v184, 1, s17
	v_lshlrev_b32_e32 v189, 2, v185
	v_lshlrev_b32_e32 v5, 2, v184
	v_readlane_b32 s23, v255, 7
	s_add_i32 s11, s60, 0
	s_add_i32 s11, s11, 0x20c00
	v_add_u32_e32 v190, s15, v5
	v_add_u32_e32 v209, s15, v187
	s_movk_i32 s15, 0x440
	v_cmp_eq_u32_e64 s[38:39], 0, v184
	s_waitcnt vmcnt(0)
	v_mul_f32_e32 v186, 0x3fb8aa3b, v2
	v_lshlrev_b32_e32 v2, 3, v0
	v_and_b32_e32 v3, 24, v2
	v_and_b32_e32 v2, 0x100, v2
	v_add3_u32 v3, v6, v3, v7
	v_add3_u32 v191, v3, v2, s10
	v_and_b32_e32 v2, 7, v0
	v_lshlrev_b32_e32 v162, 4, v2
	v_and_b32_e32 v6, -8, v0
	v_lshlrev_b32_e32 v192, 2, v2
	v_lshl_add_u64 v[2:3], s[40:41], 0, v[162:163]
	v_cmp_gt_i32_e64 s[40:41], 8, v0
	v_and_b32_e32 v0, 0xf0, v4
	v_lshl_add_u64 v[164:165], v[2:3], 0, s[28:29]
	v_add_u32_e32 v196, s17, v0
	s_movk_i32 s17, 0x70
	v_add_u32_e32 v3, 32, v187
	v_bitop3_b32 v202, v3, v4, s17 bitop3:0x78
	v_add_u32_e32 v3, 64, v187
	v_bitop3_b32 v203, v3, v4, s17 bitop3:0x78
	v_add_u32_e32 v3, 0x60, v187
	v_bitop3_b32 v204, v3, v4, s17 bitop3:0x78
	v_add_u32_e32 v3, 0x80, v187
	v_bitop3_b32 v205, v3, v4, s17 bitop3:0x78
	v_add_u32_e32 v3, 0xa0, v187
	v_bitop3_b32 v206, v3, v4, s17 bitop3:0x78
	v_add_u32_e32 v3, 0xc0, v187
	v_bitop3_b32 v207, v3, v4, s17 bitop3:0x78
	v_add_u32_e32 v3, 0xe0, v187
	v_or_b32_e32 v2, s60, v184
	v_bitop3_b32 v200, v187, v4, s17 bitop3:0x78
	v_bitop3_b32 v208, v3, v4, s17 bitop3:0x78
	v_add_u32_e32 v4, s1, v6
	s_mov_b32 s17, 0x8800
	v_add_u32_e32 v6, 0x200, v4
	v_ashrrev_i32_e32 v3, 31, v2
	s_add_i32 s10, s23, s60
	v_add_u32_e32 v163, s23, v5
	s_movk_i32 s23, 0x110
	v_mad_i64_i32 v[166:167], s[28:29], v4, s17, 0
	v_mad_i64_i32 v[168:169], s[28:29], v6, s17, 0
	v_lshl_add_u64 v[180:181], v[2:3], 2, s[54:55]
	v_or_b32_e32 v3, 1, v189
	v_mul_lo_u32 v198, v194, s23
	v_ashrrev_i32_e32 v5, 31, v4
	v_mul_lo_u32 v210, v3, s23
	s_add_u32 s28, s42, s52
	v_ashrrev_i32_e32 v7, 31, v6
	v_lshl_add_u64 v[174:175], v[4:5], 2, s[56:57]
	v_lshl_add_u64 v[176:177], v[4:5], 1, s[42:43]
	v_mul_lo_u32 v2, v185, s15
	v_add_u32_e32 v3, 0x990, v210
	v_add_u32_e32 v4, 0x440, v198
	s_addc_u32 s29, s43, s53
	v_lshl_add_u64 v[178:179], v[6:7], 1, s[42:43]
	v_lshl_add_u64 v[182:183], s[28:29], 0, v[0:1]
	v_add_u32_e32 v211, v193, v2
	v_add_u32_e32 v212, v193, v3
	v_add_u32_e32 v213, v196, v4
	v_mbcnt_lo_u32_b32 v66, -1, 0
	v_mbcnt_hi_u32_b32 v66, -1, v66
	v_add_u32_e32 v67, s1, v66
	v_ashrrev_i32_e32 v68, 4, v67
	v_and_b32_e32 v70, 0xfffff0, v68
	v_lshlrev_b32_e32 v71, 1, v68
	v_lshlrev_b32_e32 v66, 3, v66
	v_and_or_b32 v70, v71, 8, v70
	v_and_b32_e32 v69, 0x78, v66
	v_lshrrev_b32_e32 v70, 1, v70
	v_bfe_u32 v66, v66, 5, 2
	v_lshrrev_b32_e32 v71, 1, v68
	v_or_b32_e32 v66, v70, v66
	v_and_b32_e32 v70, 3, v68
	v_lshlrev_b32_e32 v69, 1, v69
	v_and_or_b32 v70, v71, 4, v70
	v_and_b32_e32 v71, 48, v69
	v_lshlrev_b32_e32 v68, 8, v68
	v_and_b32_e32 v67, 0x70, v67
	v_lshl_or_b32 v70, v70, 6, v71
	v_bitop3_b32 v67, v69, v68, v67 bitop3:0xde
	v_lshl_or_b32 v66, v66, 9, v70
	v_mov_b32_e32 v233, v67
	v_mov_b32_e32 v234, v66
	v_mbcnt_lo_u32_b32 v236, -1, 0
	v_mbcnt_hi_u32_b32 v236, -1, v236
	v_add_u32_e32 v235, s1, v236
	v_ashrrev_i32_e32 v235, 4, v235
	v_lshlrev_b32_e32 v236, 4, v236
	v_and_b32_e32 v236, 0xf0, v236
	s_mov_b32 s5, s2
	s_cmpk_lg_u32 s3, 0x100
	s_cbranch_scc1 .Lnp_s5
	s_and_b32 s5, s2, 7
	s_lshl_b32 s5, s5, 5
	s_lshr_b32 s8, s2, 3
	s_or_b32 s5, s5, s8
.Lnp_s5:
	s_add_i32 s15, s2, s3
	s_cmp_lt_i32 s15, s0
	s_cselect_b32 s15, s15, s5
	s_branch .LBB0_789
.LBB0_788:
	s_or_b64 exec, exec, s[54:55]
	s_waitcnt lgkmcnt(0)
	global_load_dword v8, v[180:181], off
	global_load_dword v7, v[180:181], off offset:128
	global_load_dword v6, v[180:181], off offset:256
	global_load_dword v0, v[180:181], off offset:384
	ds_read_b128 v[2:5], v209
	s_mov_b32 s4, s2
	s_cmpk_lg_u32 s3, 0x100
	s_cbranch_scc1 .Lnp_s4
	s_and_b32 s4, s2, 7
	s_lshl_b32 s4, s4, 5
	s_lshr_b32 s8, s2, 3
	s_or_b32 s4, s4, s8
; #define LAS __attribute__((address_space(3)))
; __device__ __forceinline__ unsigned f2bf(float f) { unsigned u = __builtin_bit_cast(unsigned, f); return (u + 0x7fffu + ((u >> 16) & 1u)) >> 16; }
; __device__ __forceinline__ int crow(int r, int hi) { return (r & 3) + 8 * (r >> 2) + 4 * hi; }
; __device__ __forceinline__ void attn_mfma(LAS unsigned char* lds, int layer, int G, const int wave_s) {
;     ...
;     for (int unit = blockIdx.x; unit < nunits; unit += G) {
;     ...
;         if (hi == 0) al_l[r32] = ra; asm volatile("s_waitcnt lgkmcnt(0)" ::: "memory");
;         { LAS unsigned char* ost = lds + AT_OST + wave * (32 * 272);
;           float gc[4];
; #pragma unroll
;           for (int d = 0; d < 4; ++d) gc[d] = gat[h * HD + 32 * d + r32];
; #pragma unroll
;           for (int r = 0; r < 16; ++r) { const int q = crow(r, hi); const float rq = al_l[q];
; #pragma unroll
;               for (int d = 0; d < 4; ++d) *(LAS bf16_t*)(ost + q * 272 + (32 * d + r32) * 2) = (bf16_t)f2bf(o[d][r] * rq * gc[d]); }
;           asm volatile("s_waitcnt lgkmcnt(0)" ::: "memory");
; #pragma unroll
;           for (int k = 0; k < 8; ++k) { const int q = k * 4 + (lane >> 4), ch = lane & 15;
;               const u32x4 v = *(const LAS u32x4*)(ost + q * 272 + ch * 16);
;               *(u32x4*)(YM + (size_t)(rowbase + q) * D + HY + h * HD + ch * 8) = v; } }
.Lnp_s4:
	s_lshl_b32 s5, s3, 1
	s_add_i32 s5, s15, s5
	s_cmp_ge_i32 s15, s3
	s_cselect_b32 s15, s4, s5
	s_cmp_lt_i32 s15, s0
	s_waitcnt lgkmcnt(0)
	v_mul_f32_e32 v9, v140, v2
	s_waitcnt vmcnt(3)
	v_mul_f32_e32 v9, v8, v9
	v_bfe_u32 v10, v9, 16, 1
	v_add3_u32 v9, v9, v10, s66
	ds_write_b16_d16_hi v211, v9
	v_mul_f32_e32 v9, v130, v2
	s_waitcnt vmcnt(2)
	v_mul_f32_e32 v9, v7, v9
	v_bfe_u32 v10, v9, 16, 1
	v_add3_u32 v9, v9, v10, s66
	ds_write_b16_d16_hi v211, v9 offset:64
	v_mul_f32_e32 v9, v128, v2
	s_waitcnt vmcnt(1)
	v_mul_f32_e32 v9, v6, v9
	v_bfe_u32 v10, v9, 16, 1
	v_mul_f32_e32 v2, v126, v2
	v_add3_u32 v9, v9, v10, s66
	s_waitcnt vmcnt(0)
	v_mul_f32_e32 v2, v0, v2
	ds_write_b16_d16_hi v211, v9 offset:128
	v_bfe_u32 v9, v2, 16, 1
	v_add3_u32 v2, v2, v9, s66
	ds_write_b16_d16_hi v211, v2 offset:192
	v_mul_f32_e32 v2, v141, v3
	v_mul_f32_e32 v2, v8, v2
	v_bfe_u32 v9, v2, 16, 1
	v_add3_u32 v2, v2, v9, s66
	v_add_u32_e32 v9, v193, v210
	ds_write_b16_d16_hi v9, v2
	v_mul_f32_e32 v2, v131, v3
	v_mul_f32_e32 v2, v7, v2
	v_bfe_u32 v10, v2, 16, 1
	v_add3_u32 v2, v2, v10, s66
	ds_write_b16_d16_hi v9, v2 offset:64
	v_mul_f32_e32 v2, v129, v3
	v_mul_f32_e32 v2, v6, v2
	v_bfe_u32 v10, v2, 16, 1
	v_add3_u32 v2, v2, v10, s66
	ds_write_b16_d16_hi v9, v2 offset:128
	v_mul_f32_e32 v2, v127, v3
	v_mul_f32_e32 v2, v0, v2
	v_bfe_u32 v3, v2, 16, 1
	v_add3_u32 v2, v2, v3, s66
	ds_write_b16_d16_hi v9, v2 offset:192
	v_mul_f32_e32 v2, v138, v4
	v_mul_f32_e32 v2, v8, v2
	v_bfe_u32 v3, v2, 16, 1
	v_add3_u32 v2, v2, v3, s66
	ds_write_b16_d16_hi v9, v2 offset:272
	v_mul_f32_e32 v2, v134, v4
	v_mul_f32_e32 v2, v7, v2
	v_bfe_u32 v3, v2, 16, 1
	v_add3_u32 v2, v2, v3, s66
	ds_write_b16_d16_hi v9, v2 offset:336
	v_mul_f32_e32 v2, v136, v4
	v_mul_f32_e32 v2, v6, v2
	v_bfe_u32 v3, v2, 16, 1
	v_add3_u32 v2, v2, v3, s66
	ds_write_b16_d16_hi v9, v2 offset:400
	v_mul_f32_e32 v2, v132, v4
	v_mul_f32_e32 v2, v0, v2
	v_bfe_u32 v3, v2, 16, 1
	v_add3_u32 v2, v2, v3, s66
	ds_write_b16_d16_hi v9, v2 offset:464
	v_mul_f32_e32 v2, v139, v5
	v_mul_f32_e32 v2, v8, v2
	v_bfe_u32 v3, v2, 16, 1
	v_add3_u32 v2, v2, v3, s66
	ds_write_b16_d16_hi v9, v2 offset:544
	v_mul_f32_e32 v2, v135, v5
	v_mul_f32_e32 v2, v7, v2
	v_bfe_u32 v3, v2, 16, 1
	v_add3_u32 v2, v2, v3, s66
	ds_write_b16_d16_hi v9, v2 offset:608
	v_mul_f32_e32 v2, v137, v5
	v_mul_f32_e32 v2, v6, v2
	v_bfe_u32 v3, v2, 16, 1
	v_add3_u32 v2, v2, v3, s66
	ds_write_b16_d16_hi v9, v2 offset:672
	v_mul_f32_e32 v2, v133, v5
	v_mul_f32_e32 v2, v0, v2
	v_bfe_u32 v3, v2, 16, 1
	v_add3_u32 v2, v2, v3, s66
	ds_write_b16_d16_hi v9, v2 offset:736
	ds_read_b128 v[2:5], v209 offset:32
	s_waitcnt lgkmcnt(0)
	v_mul_f32_e32 v10, v100, v2
	v_mul_f32_e32 v10, v8, v10
	v_bfe_u32 v11, v10, 16, 1
	v_add3_u32 v10, v10, v11, s66
	ds_write_b16_d16_hi v9, v10 offset:1904
	v_mul_f32_e32 v10, v96, v2
	v_mul_f32_e32 v10, v7, v10
	v_bfe_u32 v11, v10, 16, 1
	v_add3_u32 v10, v10, v11, s66
	ds_write_b16_d16_hi v9, v10 offset:1968
	v_mul_f32_e32 v10, v98, v2
	v_mul_f32_e32 v10, v6, v10
	v_bfe_u32 v11, v10, 16, 1
	v_mul_f32_e32 v2, v94, v2
	v_add3_u32 v10, v10, v11, s66
	v_mul_f32_e32 v2, v0, v2
	ds_write_b16_d16_hi v9, v10 offset:2032
	v_bfe_u32 v10, v2, 16, 1
	v_add3_u32 v2, v2, v10, s66
	ds_write_b16_d16_hi v9, v2 offset:2096
	v_mul_f32_e32 v2, v101, v3
	v_mul_f32_e32 v2, v8, v2
	v_bfe_u32 v10, v2, 16, 1
	v_add3_u32 v2, v2, v10, s66
	ds_write_b16_d16_hi v9, v2 offset:2176
	v_mul_f32_e32 v2, v97, v3
	v_mul_f32_e32 v2, v7, v2
	v_bfe_u32 v10, v2, 16, 1
	v_add3_u32 v2, v2, v10, s66
	ds_write_b16_d16_hi v9, v2 offset:2240
	v_mul_f32_e32 v2, v99, v3
	v_mul_f32_e32 v2, v6, v2
	v_bfe_u32 v10, v2, 16, 1
	v_add3_u32 v2, v2, v10, s66
	ds_write_b16_d16_hi v9, v2 offset:2304
	v_mul_f32_e32 v2, v95, v3
	v_mul_f32_e32 v2, v0, v2
	v_bfe_u32 v3, v2, 16, 1
	v_add3_u32 v2, v2, v3, s66
	ds_write_b16_d16_hi v9, v2 offset:2368
	v_mul_f32_e32 v2, v108, v4
	v_mul_f32_e32 v2, v8, v2
	v_bfe_u32 v3, v2, 16, 1
	v_add3_u32 v2, v2, v3, s66
	ds_write_b16_d16_hi v9, v2 offset:2448
	v_mul_f32_e32 v2, v104, v4
	v_mul_f32_e32 v2, v7, v2
	v_bfe_u32 v3, v2, 16, 1
	v_add3_u32 v2, v2, v3, s66
	ds_write_b16_d16_hi v212, v2 offset:64
	v_mul_f32_e32 v2, v106, v4
	v_mul_f32_e32 v2, v6, v2
	v_bfe_u32 v3, v2, 16, 1
	v_add3_u32 v2, v2, v3, s66
	ds_write_b16_d16_hi v212, v2 offset:128
	v_mul_f32_e32 v2, v102, v4
	v_mul_f32_e32 v2, v0, v2
	v_bfe_u32 v3, v2, 16, 1
	v_add3_u32 v2, v2, v3, s66
	ds_write_b16_d16_hi v212, v2 offset:192
	v_mul_f32_e32 v2, v109, v5
	v_mul_f32_e32 v2, v8, v2
	v_bfe_u32 v3, v2, 16, 1
	v_add3_u32 v2, v2, v3, s66
	ds_write_b16_d16_hi v212, v2 offset:272
	v_mul_f32_e32 v2, v105, v5
	v_mul_f32_e32 v2, v7, v2
	v_bfe_u32 v3, v2, 16, 1
	v_add3_u32 v2, v2, v3, s66
	ds_write_b16_d16_hi v212, v2 offset:336
	v_mul_f32_e32 v2, v107, v5
	v_mul_f32_e32 v2, v6, v2
	v_bfe_u32 v3, v2, 16, 1
	v_add3_u32 v2, v2, v3, s66
	ds_write_b16_d16_hi v212, v2 offset:400
	v_mul_f32_e32 v2, v103, v5
	v_mul_f32_e32 v2, v0, v2
	v_bfe_u32 v3, v2, 16, 1
	v_add3_u32 v2, v2, v3, s66
	ds_write_b16_d16_hi v212, v2 offset:464
	ds_read_b128 v[2:5], v209 offset:64
	s_waitcnt lgkmcnt(0)
; #define LAS __attribute__((address_space(3)))
; __device__ __forceinline__ unsigned f2bf(float f) { unsigned u = __builtin_bit_cast(unsigned, f); return (u + 0x7fffu + ((u >> 16) & 1u)) >> 16; }
; __device__ __forceinline__ int crow(int r, int hi) { return (r & 3) + 8 * (r >> 2) + 4 * hi; }
; __device__ __forceinline__ void attn_mfma(LAS unsigned char* lds, int layer, int G, const int wave_s) {
;     ...
;         { LAS unsigned char* ost = lds + AT_OST + wave * (32 * 272);
;           float gc[4];
; #pragma unroll
;           for (int d = 0; d < 4; ++d) gc[d] = gat[h * HD + 32 * d + r32];
; #pragma unroll
;           for (int r = 0; r < 16; ++r) { const int q = crow(r, hi); const float rq = al_l[q];
; #pragma unroll
;               for (int d = 0; d < 4; ++d) *(LAS bf16_t*)(ost + q * 272 + (32 * d + r32) * 2) = (bf16_t)f2bf(o[d][r] * rq * gc[d]); }
;           asm volatile("s_waitcnt lgkmcnt(0)" ::: "memory");
; #pragma unroll
;           for (int k = 0; k < 8; ++k) { const int q = k * 4 + (lane >> 4), ch = lane & 15;
;               const u32x4 v = *(const LAS u32x4*)(ost + q * 272 + ch * 16);
;               *(u32x4*)(YM + (size_t)(rowbase + q) * D + HY + h * HD + ch * 8) = v; } }
	v_mul_f32_e32 v9, v124, v2
	v_mul_f32_e32 v9, v8, v9
	v_bfe_u32 v10, v9, 16, 1
	v_add3_u32 v9, v9, v10, s66
	ds_write_b16_d16_hi v212, v9 offset:1632
	v_mul_f32_e32 v9, v122, v2
	v_mul_f32_e32 v9, v7, v9
	v_bfe_u32 v10, v9, 16, 1
	v_add3_u32 v9, v9, v10, s66
	ds_write_b16_d16_hi v212, v9 offset:1696
	v_mul_f32_e32 v9, v120, v2
	v_mul_f32_e32 v9, v6, v9
	v_bfe_u32 v10, v9, 16, 1
	v_mul_f32_e32 v2, v118, v2
	v_add3_u32 v9, v9, v10, s66
	v_mul_f32_e32 v2, v0, v2
	ds_write_b16_d16_hi v212, v9 offset:1760
	v_bfe_u32 v9, v2, 16, 1
	v_add3_u32 v2, v2, v9, s66
	ds_write_b16_d16_hi v212, v2 offset:1824
	v_mul_f32_e32 v2, v125, v3
	v_mul_f32_e32 v2, v8, v2
	v_bfe_u32 v9, v2, 16, 1
	v_add3_u32 v2, v2, v9, s66
	ds_write_b16_d16_hi v212, v2 offset:1904
	v_mul_f32_e32 v2, v123, v3
	v_mul_f32_e32 v2, v7, v2
	v_bfe_u32 v9, v2, 16, 1
	v_add3_u32 v2, v2, v9, s66
	ds_write_b16_d16_hi v212, v2 offset:1968
	v_mul_f32_e32 v2, v121, v3
	v_mul_f32_e32 v2, v6, v2
	v_bfe_u32 v9, v2, 16, 1
	v_add3_u32 v2, v2, v9, s66
	ds_write_b16_d16_hi v212, v2 offset:2032
	v_mul_f32_e32 v2, v119, v3
	v_mul_f32_e32 v2, v0, v2
	v_bfe_u32 v3, v2, 16, 1
	v_add3_u32 v2, v2, v3, s66
	ds_write_b16_d16_hi v212, v2 offset:2096
	v_mul_f32_e32 v2, v116, v4
	v_mul_f32_e32 v2, v8, v2
	v_bfe_u32 v3, v2, 16, 1
	v_add3_u32 v2, v2, v3, s66
	ds_write_b16_d16_hi v212, v2 offset:2176
	v_mul_f32_e32 v2, v114, v4
	v_mul_f32_e32 v2, v7, v2
	v_bfe_u32 v3, v2, 16, 1
	v_add3_u32 v2, v2, v3, s66
	ds_write_b16_d16_hi v212, v2 offset:2240
	v_mul_f32_e32 v2, v112, v4
	v_mul_f32_e32 v2, v6, v2
	v_bfe_u32 v3, v2, 16, 1
	v_add3_u32 v2, v2, v3, s66
	ds_write_b16_d16_hi v212, v2 offset:2304
	v_mul_f32_e32 v2, v110, v4
	v_mul_f32_e32 v2, v0, v2
	v_bfe_u32 v3, v2, 16, 1
	v_add3_u32 v2, v2, v3, s66
	ds_write_b16_d16_hi v212, v2 offset:2368
	v_mul_f32_e32 v2, v117, v5
	v_mul_f32_e32 v2, v8, v2
	v_bfe_u32 v3, v2, 16, 1
	v_add3_u32 v2, v2, v3, s66
	ds_write_b16_d16_hi v212, v2 offset:2448
	v_mul_f32_e32 v2, v115, v5
	v_mul_f32_e32 v2, v7, v2
	v_bfe_u32 v3, v2, 16, 1
	v_add3_u32 v2, v2, v3, s66
	ds_write_b16_d16_hi v212, v2 offset:2512
	v_mul_f32_e32 v2, v113, v5
	v_mul_f32_e32 v2, v6, v2
	v_bfe_u32 v3, v2, 16, 1
	v_add3_u32 v2, v2, v3, s66
	ds_write_b16_d16_hi v212, v2 offset:2576
	v_mul_f32_e32 v2, v111, v5
	v_mul_f32_e32 v2, v0, v2
	v_bfe_u32 v3, v2, 16, 1
	v_add3_u32 v2, v2, v3, s66
	ds_write_b16_d16_hi v212, v2 offset:2640
	ds_read_b128 v[2:5], v209 offset:96
	s_waitcnt lgkmcnt(0)
	v_mul_f32_e32 v9, v84, v2
	v_mul_f32_e32 v9, v8, v9
	v_bfe_u32 v10, v9, 16, 1
	v_add3_u32 v9, v9, v10, s66
	ds_write_b16_d16_hi v212, v9 offset:3808
	v_mul_f32_e32 v9, v80, v2
	v_mul_f32_e32 v9, v7, v9
	v_bfe_u32 v10, v9, 16, 1
	v_add3_u32 v9, v9, v10, s66
	ds_write_b16_d16_hi v212, v9 offset:3872
	v_mul_f32_e32 v9, v82, v2
	v_mul_f32_e32 v9, v6, v9
	v_bfe_u32 v10, v9, 16, 1
	v_mul_f32_e32 v2, v78, v2
	v_add3_u32 v9, v9, v10, s66
	v_mul_f32_e32 v2, v0, v2
	ds_write_b16_d16_hi v212, v9 offset:3936
	v_bfe_u32 v9, v2, 16, 1
	v_add3_u32 v2, v2, v9, s66
	ds_write_b16_d16_hi v212, v2 offset:4000
	v_mul_f32_e32 v2, v85, v3
	v_mul_f32_e32 v2, v8, v2
	v_bfe_u32 v9, v2, 16, 1
	v_add3_u32 v2, v2, v9, s66
	ds_write_b16_d16_hi v212, v2 offset:4080
	v_mul_f32_e32 v2, v81, v3
	v_mul_f32_e32 v2, v7, v2
	v_bfe_u32 v9, v2, 16, 1
	v_add3_u32 v2, v2, v9, s66
	ds_write_b16_d16_hi v212, v2 offset:4144
	v_mul_f32_e32 v2, v83, v3
	v_mul_f32_e32 v2, v6, v2
	v_bfe_u32 v9, v2, 16, 1
	v_add3_u32 v2, v2, v9, s66
	ds_write_b16_d16_hi v212, v2 offset:4208
	v_mul_f32_e32 v2, v79, v3
	v_mul_f32_e32 v2, v0, v2
	v_bfe_u32 v3, v2, 16, 1
	v_add3_u32 v2, v2, v3, s66
	ds_write_b16_d16_hi v212, v2 offset:4272
	v_mul_f32_e32 v2, v92, v4
	v_mul_f32_e32 v2, v8, v2
	v_bfe_u32 v3, v2, 16, 1
	v_add3_u32 v2, v2, v3, s66
	ds_write_b16_d16_hi v212, v2 offset:4352
	v_mul_f32_e32 v2, v88, v4
	v_mul_f32_e32 v2, v7, v2
	v_bfe_u32 v3, v2, 16, 1
	v_add3_u32 v2, v2, v3, s66
	ds_write_b16_d16_hi v212, v2 offset:4416
	v_mul_f32_e32 v2, v90, v4
	v_mul_f32_e32 v2, v6, v2
	v_bfe_u32 v3, v2, 16, 1
	v_add3_u32 v2, v2, v3, s66
	ds_write_b16_d16_hi v212, v2 offset:4480
	v_mul_f32_e32 v2, v86, v4
	v_mul_f32_e32 v2, v0, v2
	v_bfe_u32 v3, v2, 16, 1
	v_add3_u32 v2, v2, v3, s66
	ds_write_b16_d16_hi v212, v2 offset:4544
	v_mul_f32_e32 v2, v93, v5
	v_mul_f32_e32 v2, v8, v2
	v_bfe_u32 v3, v2, 16, 1
	v_add3_u32 v2, v2, v3, s66
	ds_write_b16_d16_hi v212, v2 offset:4624
	v_mul_f32_e32 v2, v89, v5
	v_mul_f32_e32 v2, v7, v2
	v_bfe_u32 v3, v2, 16, 1
	v_add3_u32 v2, v2, v3, s66
	ds_write_b16_d16_hi v212, v2 offset:4688
	v_mul_f32_e32 v2, v91, v5
	v_mul_f32_e32 v2, v6, v2
	v_bfe_u32 v3, v2, 16, 1
	v_add3_u32 v2, v2, v3, s66
	ds_write_b16_d16_hi v212, v2 offset:4752
	v_mul_f32_e32 v2, v87, v5
	v_mul_f32_e32 v0, v0, v2
	v_bfe_u32 v2, v0, 16, 1
	v_add3_u32 v0, v0, v2, s66
	ds_write_b16_d16_hi v212, v0 offset:4816
	s_waitcnt lgkmcnt(0)
	v_add_u32_e32 v0, v196, v198
	ds_read_b128 v[2:5], v0
	v_add_u32_e32 v6, s52, v194
	v_ashrrev_i32_e32 v7, 31, v6
	v_lshlrev_b64 v[8:9], 12, v[6:7]
	v_lshl_add_u64 v[8:9], v[182:183], 0, v[8:9]
	s_waitcnt lgkmcnt(0)
	global_store_dwordx4 v[8:9], v[2:5], off offset:2048
	ds_read_b128 v[2:5], v213
	v_add_u32_e32 v0, 4, v194
	v_add_u32_e32 v8, s52, v0
	v_ashrrev_i32_e32 v9, 31, v8
	v_lshlrev_b64 v[8:9], 12, v[8:9]
	v_lshl_add_u64 v[8:9], v[182:183], 0, v[8:9]
	s_waitcnt lgkmcnt(0)
	global_store_dwordx4 v[8:9], v[2:5], off offset:2048
	ds_read_b128 v[2:5], v213 offset:1088
	v_add_u32_e32 v8, 8, v6
	v_ashrrev_i32_e32 v9, 31, v8
	v_lshlrev_b64 v[8:9], 12, v[8:9]
	v_lshl_add_u64 v[8:9], v[182:183], 0, v[8:9]
	s_waitcnt lgkmcnt(0)
	global_store_dwordx4 v[8:9], v[2:5], off offset:2048
	ds_read_b128 v[2:5], v213 offset:2176
	v_add_u32_e32 v8, 12, v6
	v_ashrrev_i32_e32 v9, 31, v8
	v_lshlrev_b64 v[8:9], 12, v[8:9]
	v_lshl_add_u64 v[8:9], v[182:183], 0, v[8:9]
	s_waitcnt lgkmcnt(0)
	global_store_dwordx4 v[8:9], v[2:5], off offset:2048
	ds_read_b128 v[2:5], v213 offset:3264
	v_add_u32_e32 v8, 16, v6
	v_ashrrev_i32_e32 v9, 31, v8
	v_lshlrev_b64 v[8:9], 12, v[8:9]
	v_lshl_add_u64 v[8:9], v[182:183], 0, v[8:9]
	s_waitcnt lgkmcnt(0)
	global_store_dwordx4 v[8:9], v[2:5], off offset:2048
	ds_read_b128 v[2:5], v213 offset:4352
	v_add_u32_e32 v8, 20, v6
	v_ashrrev_i32_e32 v9, 31, v8
	v_lshlrev_b64 v[8:9], 12, v[8:9]
	v_lshl_add_u64 v[8:9], v[182:183], 0, v[8:9]
	s_waitcnt lgkmcnt(0)
	global_store_dwordx4 v[8:9], v[2:5], off offset:2048
	ds_read_b128 v[2:5], v213 offset:5440
	v_add_u32_e32 v8, 24, v6
	v_ashrrev_i32_e32 v9, 31, v8
	v_lshlrev_b64 v[8:9], 12, v[8:9]
	v_lshl_add_u64 v[8:9], v[182:183], 0, v[8:9]
	s_waitcnt lgkmcnt(0)
	global_store_dwordx4 v[8:9], v[2:5], off offset:2048
	ds_read_b128 v[2:5], v213 offset:6528
	v_add_u32_e32 v6, 28, v6
	v_ashrrev_i32_e32 v7, 31, v6
	v_lshlrev_b64 v[6:7], 12, v[6:7]
	v_lshl_add_u64 v[6:7], v[182:183], 0, v[6:7]
	s_waitcnt lgkmcnt(0)
	global_store_dwordx4 v[6:7], v[2:5], off offset:2048
	s_cbranch_scc0 .LBB0_826
